# speedup vs baseline: 1.0045x; 1.0045x over previous
; __device__ __forceinline__ void phase_fox_attn(const Params& p, char* smem) {
;     ...
; #pragma unroll
;       for (int qb = 0; qb < 2; ++qb) {
;         const float mu = (m[qb] == -INFINITY) ? 0.f : m[qb];
;         float ps = 0.f;
; #pragma unroll
;         for (int kb = 0; kb < 4; ++kb)
; #pragma unroll
;           for (int r = 0; r < 4; ++r) {
;             float pv = __builtin_amdgcn_exp2f(s[kb][qb][r] - mu);
;             s[kb][qb][r] = pv;
;             ps += pv;
;           }
;         l[qb] += ps;
;       }
;       __builtin_amdgcn_s_setprio(1);
; #pragma unroll
;       for (int kp = 0; kp < 2; ++kp) {
;         bf16x8 pf[2];
; #pragma unroll
;         for (int qb = 0; qb < 2; ++qb) {
;           u32x4 u;
;           u.x = pack2(s[2 * kp][qb][0], s[2 * kp][qb][1]); u.y = pack2(s[2 * kp][qb][2], s[2 * kp][qb][3]);
;           u.z = pack2(s[2 * kp + 1][qb][0], s[2 * kp + 1][qb][1]); u.w = pack2(s[2 * kp + 1][qb][2], s[2 * kp + 1][qb][3]);
;           pf[qb] = *(bf16x8*)&u;
;         }
;         const int vo0 = vb_ ^ ((kp * 4) << 4), vo1 = vb_ ^ ((kp * 4 + 2) << 4);
; #pragma unroll
;         for (int db = 0; db < 8; ++db) {
;           u32x2 v0 = *(const u32x2*)(sV + db * 2048 + vo0);
;           u32x2 v1 = *(const u32x2*)(sV + db * 2048 + vo1);
;           u32x4 u; u.x = v0.x; u.y = v0.y; u.z = v1.x; u.w = v1.y;
;           bf16x8 a = *(bf16x8*)&u;
;           o[db][0] = __builtin_amdgcn_mfma_f32_16x16x32_bf16(a, pf[0], o[db][0], 0, 0, 0);
;           o[db][1] = __builtin_amdgcn_mfma_f32_16x16x32_bf16(a, pf[1], o[db][1], 0, 0, 0);
;         }
.LBB0_200:
	v_cmp_neq_f32_e32 vcc, s0, v138
	s_nop 1
	v_cndmask_b32_e32 v168, 0, v138, vcc
	v_sub_f32_e32 v139, v139, v168
	v_exp_f32_e32 v169, v139
	v_sub_f32_e32 v139, v143, v168
	v_exp_f32_e32 v171, v139
	v_sub_f32_e32 v139, v145, v168
	v_exp_f32_e32 v173, v139
	v_sub_f32_e32 v139, v146, v168
	v_exp_f32_e32 v175, v139
	v_sub_f32_e32 v139, v147, v168
	v_exp_f32_e32 v177, v139
	v_sub_f32_e32 v139, v148, v168
	v_exp_f32_e32 v179, v139
	v_sub_f32_e32 v139, v149, v168
	v_exp_f32_e32 v181, v139
	v_sub_f32_e32 v139, v150, v168
	v_exp_f32_e32 v183, v139
	v_sub_f32_e32 v139, v151, v168
	v_exp_f32_e32 v185, v139
	v_sub_f32_e32 v139, v152, v168
	v_exp_f32_e32 v187, v139
	v_sub_f32_e32 v139, v153, v168
	v_exp_f32_e32 v189, v139
	v_sub_f32_e32 v139, v154, v168
	v_exp_f32_e32 v191, v139
	v_sub_f32_e32 v139, v155, v168
	v_exp_f32_e32 v155, v139
	v_sub_f32_e32 v139, v157, v168
	v_exp_f32_e32 v193, v139
	v_sub_f32_e32 v139, v158, v168
	v_exp_f32_e32 v195, v139
	v_sub_f32_e32 v139, v159, v168
	v_cmp_neq_f32_e32 vcc, s0, v137
	v_exp_f32_e32 v197, v139
	s_nop 0
	v_cndmask_b32_e32 v139, 0, v137, vcc
	v_sub_f32_e32 v143, v160, v139
	v_exp_f32_e32 v168, v143
	v_sub_f32_e32 v143, v161, v139
	v_exp_f32_e32 v170, v143
	v_sub_f32_e32 v143, v164, v139
	v_exp_f32_e32 v172, v143
	v_sub_f32_e32 v143, v165, v139
	v_exp_f32_e32 v174, v143
	v_sub_f32_e32 v143, v166, v139
	v_exp_f32_e32 v176, v143
	v_sub_f32_e32 v143, v167, v139
	v_pk_add_f32 v[146:147], v[168:169], 0 op_sel_hi:[1,0]
	v_exp_f32_e32 v178, v143
	v_pk_add_f32 v[146:147], v[170:171], v[146:147]
	v_sub_f32_e32 v143, v162, v139
	v_pk_add_f32 v[146:147], v[172:173], v[146:147]
	v_exp_f32_e32 v180, v143
	v_sub_f32_e32 v143, v163, v139
	v_sub_f32_e32 v96, v96, v139
	v_pk_add_f32 v[146:147], v[174:175], v[146:147]
	v_exp_f32_e32 v182, v143
	v_sub_f32_e32 v100, v100, v139
	v_exp_f32_e32 v154, v96
	v_sub_f32_e32 v96, v97, v139
	v_pk_add_f32 v[146:147], v[176:177], v[146:147]
	v_exp_f32_e32 v184, v100
	v_sub_f32_e32 v100, v101, v139
	v_exp_f32_e32 v192, v96
	v_sub_f32_e32 v96, v98, v139
	v_pk_add_f32 v[146:147], v[178:179], v[146:147]
	v_exp_f32_e32 v186, v100
	v_sub_f32_e32 v100, v102, v139
	v_exp_f32_e32 v194, v96
	v_sub_f32_e32 v96, v99, v139
	v_exp_f32_e32 v188, v100
	v_sub_f32_e32 v100, v103, v139
	v_exp_f32_e32 v196, v96
	v_pk_add_f32 v[96:97], v[180:181], v[146:147]
	v_exp_f32_e32 v190, v100
	v_pk_add_f32 v[96:97], v[182:183], v[96:97]
	s_nop 0
	v_pk_add_f32 v[96:97], v[184:185], v[96:97]
	s_nop 0
	v_pk_add_f32 v[96:97], v[186:187], v[96:97]
	s_nop 0
	v_pk_add_f32 v[96:97], v[188:189], v[96:97]
	s_nop 0
	v_pk_add_f32 v[96:97], v[190:191], v[96:97]
	s_nop 0
	v_pk_add_f32 v[96:97], v[154:155], v[96:97]
	s_nop 0
	v_pk_add_f32 v[96:97], v[192:193], v[96:97]
	s_nop 0
	v_pk_add_f32 v[96:97], v[194:195], v[96:97]
	s_nop 0
	v_pk_add_f32 v[96:97], v[196:197], v[96:97]
	s_nop 0
	v_pk_add_f32 v[108:109], v[108:109], v[96:97]
	s_setprio 1
	v_add_u32_e32 v139, s6, v104
	v_xad_u32 v143, v104, 32, s6
	ds_read_b64 v[150:151], v139 offset:32768
	ds_read_b64 v[152:153], v143 offset:32768
	ds_read_b64 v[100:101], v139 offset:34816
	ds_read_b64 v[102:103], v143 offset:34816
	v_cvt_pk_bf16_f32 v146, v169, v171
	v_cvt_pk_bf16_f32 v147, v173, v175
	v_cvt_pk_bf16_f32 v148, v177, v179
	v_cvt_pk_bf16_f32 v149, v181, v183
	v_cvt_pk_bf16_f32 v158, v168, v170
	v_cvt_pk_bf16_f32 v159, v172, v174
	v_cvt_pk_bf16_f32 v160, v176, v178
	v_cvt_pk_bf16_f32 v161, v180, v182
	s_waitcnt lgkmcnt(2)
	v_mfma_f32_16x16x32_bf16 v[48:51], v[150:153], v[146:149], v[48:51]
	v_mfma_f32_16x16x32_bf16 v[28:31], v[150:153], v[158:161], v[28:31]
	ds_read_b64 v[96:97], v139 offset:36864
	ds_read_b64 v[98:99], v143 offset:36864
	ds_read_b64 v[150:151], v139 offset:38912
	ds_read_b64 v[152:153], v143 offset:38912
	s_waitcnt lgkmcnt(4)
; __device__ __forceinline__ void phase_fox_attn(const Params& p, char* smem) {
;     ...
;       for (int kp = 0; kp < 2; ++kp) {
;         bf16x8 pf[2];
; #pragma unroll
;         for (int qb = 0; qb < 2; ++qb) {
;           u32x4 u;
;           u.x = pack2(s[2 * kp][qb][0], s[2 * kp][qb][1]); u.y = pack2(s[2 * kp][qb][2], s[2 * kp][qb][3]);
;           u.z = pack2(s[2 * kp + 1][qb][0], s[2 * kp + 1][qb][1]); u.w = pack2(s[2 * kp + 1][qb][2], s[2 * kp + 1][qb][3]);
;           pf[qb] = *(bf16x8*)&u;
;         }
;         const int vo0 = vb_ ^ ((kp * 4) << 4), vo1 = vb_ ^ ((kp * 4 + 2) << 4);
; #pragma unroll
;         for (int db = 0; db < 8; ++db) {
;           u32x2 v0 = *(const u32x2*)(sV + db * 2048 + vo0);
;           u32x2 v1 = *(const u32x2*)(sV + db * 2048 + vo1);
;           u32x4 u; u.x = v0.x; u.y = v0.y; u.z = v1.x; u.w = v1.y;
;           bf16x8 a = *(bf16x8*)&u;
;           o[db][0] = __builtin_amdgcn_mfma_f32_16x16x32_bf16(a, pf[0], o[db][0], 0, 0, 0);
;           o[db][1] = __builtin_amdgcn_mfma_f32_16x16x32_bf16(a, pf[1], o[db][1], 0, 0, 0);
;         }
;       }
;       __builtin_amdgcn_s_setprio(0);
;     }
	v_mfma_f32_16x16x32_bf16 v[52:55], v[100:103], v[146:149], v[52:55]
	v_mfma_f32_16x16x32_bf16 v[24:27], v[100:103], v[158:161], v[24:27]
	s_waitcnt lgkmcnt(2)
	v_mfma_f32_16x16x32_bf16 v[56:59], v[96:99], v[146:149], v[56:59]
	v_mfma_f32_16x16x32_bf16 v[20:23], v[96:99], v[158:161], v[20:23]
	ds_read_b64 v[100:101], v139 offset:40960
	ds_read_b64 v[102:103], v143 offset:40960
	ds_read_b64 v[96:97], v139 offset:43008
	ds_read_b64 v[98:99], v143 offset:43008
	s_waitcnt lgkmcnt(4)
	v_mfma_f32_16x16x32_bf16 v[60:63], v[150:153], v[146:149], v[60:63]
	v_mfma_f32_16x16x32_bf16 v[16:19], v[150:153], v[158:161], v[16:19]
	s_waitcnt lgkmcnt(2)
	v_mfma_f32_16x16x32_bf16 v[44:47], v[100:103], v[146:149], v[44:47]
	v_mfma_f32_16x16x32_bf16 v[12:15], v[100:103], v[158:161], v[12:15]
	ds_read_b64 v[150:151], v139 offset:45056
	ds_read_b64 v[152:153], v143 offset:45056
	ds_read_b64 v[100:101], v139 offset:47104
	ds_read_b64 v[102:103], v143 offset:47104
	s_waitcnt lgkmcnt(4)
	v_mfma_f32_16x16x32_bf16 v[40:43], v[96:99], v[146:149], v[40:43]
	v_mfma_f32_16x16x32_bf16 v[8:11], v[96:99], v[158:161], v[8:11]
	s_waitcnt lgkmcnt(2)
	v_mfma_f32_16x16x32_bf16 v[36:39], v[150:153], v[146:149], v[36:39]
	v_mfma_f32_16x16x32_bf16 v[4:7], v[150:153], v[158:161], v[4:7]
	v_xor_b32_e32 v143, 0x60, v104
	v_xad_u32 v104, v104, 64, s6
	v_add_u32_e32 v139, s6, v143
	ds_read_b64 v[96:97], v104 offset:32768
	ds_read_b64 v[98:99], v139 offset:32768
	ds_read_b64 v[150:151], v104 offset:34816
	ds_read_b64 v[152:153], v139 offset:34816
	s_waitcnt lgkmcnt(4)
	v_mfma_f32_16x16x32_bf16 v[32:35], v[100:103], v[146:149], v[32:35]
	v_cvt_pk_bf16_f32 v146, v185, v187
	v_cvt_pk_bf16_f32 v147, v189, v191
	v_cvt_pk_bf16_f32 v148, v155, v193
	v_cvt_pk_bf16_f32 v149, v195, v197
	v_mfma_f32_16x16x32_bf16 v[0:3], v[100:103], v[158:161], v[0:3]
	v_cvt_pk_bf16_f32 v158, v184, v186
	v_cvt_pk_bf16_f32 v159, v188, v190
	v_cvt_pk_bf16_f32 v160, v154, v192
	v_cvt_pk_bf16_f32 v161, v194, v196
	s_waitcnt lgkmcnt(2)
	v_mfma_f32_16x16x32_bf16 v[48:51], v[96:99], v[146:149], v[48:51]
	v_mfma_f32_16x16x32_bf16 v[28:31], v[96:99], v[158:161], v[28:31]
	ds_read_b64 v[100:101], v104 offset:36864
	ds_read_b64 v[102:103], v139 offset:36864
	ds_read_b64 v[96:97], v104 offset:38912
	ds_read_b64 v[98:99], v139 offset:38912
	s_waitcnt lgkmcnt(4)
	v_mfma_f32_16x16x32_bf16 v[52:55], v[150:153], v[146:149], v[52:55]
	v_mfma_f32_16x16x32_bf16 v[24:27], v[150:153], v[158:161], v[24:27]
	s_waitcnt lgkmcnt(2)
	v_mfma_f32_16x16x32_bf16 v[56:59], v[100:103], v[146:149], v[56:59]
	v_mfma_f32_16x16x32_bf16 v[20:23], v[100:103], v[158:161], v[20:23]
	ds_read_b64 v[150:151], v104 offset:40960
	ds_read_b64 v[152:153], v139 offset:40960
	ds_read_b64 v[100:101], v104 offset:43008
	ds_read_b64 v[102:103], v139 offset:43008
	s_waitcnt lgkmcnt(4)
	v_mfma_f32_16x16x32_bf16 v[60:63], v[96:99], v[146:149], v[60:63]
	v_mfma_f32_16x16x32_bf16 v[16:19], v[96:99], v[158:161], v[16:19]
	s_waitcnt lgkmcnt(2)
	v_mfma_f32_16x16x32_bf16 v[44:47], v[150:153], v[146:149], v[44:47]
	v_mfma_f32_16x16x32_bf16 v[12:15], v[150:153], v[158:161], v[12:15]
	ds_read_b64 v[96:97], v104 offset:45056
	ds_read_b64 v[98:99], v139 offset:45056
	ds_read_b64 v[150:151], v104 offset:47104
	ds_read_b64 v[152:153], v139 offset:47104
	s_waitcnt lgkmcnt(4)
	v_mfma_f32_16x16x32_bf16 v[40:43], v[100:103], v[146:149], v[40:43]
	v_mfma_f32_16x16x32_bf16 v[8:11], v[100:103], v[158:161], v[8:11]
	s_waitcnt lgkmcnt(2)
	v_mfma_f32_16x16x32_bf16 v[36:39], v[96:99], v[146:149], v[36:39]
	v_mfma_f32_16x16x32_bf16 v[4:7], v[96:99], v[158:161], v[4:7]
	s_waitcnt lgkmcnt(0)
	v_mfma_f32_16x16x32_bf16 v[32:35], v[150:153], v[146:149], v[32:35]
	v_mfma_f32_16x16x32_bf16 v[0:3], v[150:153], v[158:161], v[0:3]
	s_setprio 0
	s_add_i32 s85, s85, 1
	s_add_i32 s84, s84, -1
	s_sub_i32 s86, s86, 64
	s_cmp_eq_u32 s35, s85
	s_cbranch_scc1 .LBB0_194
